# out-projection residual epilogue double-buffered (next block's 4 loads in flight during fma+store) + barrier early-acquire + combine hoist
# speedup vs baseline: 1.0321x; 1.0068x over previous
;     __device__ __forceinline__ void operator()(const pg8::f32x4 (&acc)[2][2][4][2], const pg8::Unit& u, int wr, int wc, int fr, int fq) const {
;         const int row0 = u.pm * 256 + wr * 64 + fr, col0 = u.pn * 256 + wc * 32 + 4 * fq;
;         const float* gp = gate + (size_t)(u.pm >> 4) * 6144 + col0;
;         pg8::f32x4 gv[2][2];
; #pragma unroll
;         for (int bj = 0; bj < 2; ++bj)
; #pragma unroll
;             for (int n = 0; n < 2; ++n) gv[bj][n] = *(const pg8::f32x4*)(gp + bj * 128 + n * 16);
; #pragma unroll
;         for (int ai = 0; ai < 2; ++ai)
; #pragma unroll
;             for (int m = 0; m < 4; ++m) { const size_t ro = (size_t)(row0 + ai * 128 + m * 16) * DM + col0;
; #pragma unroll
;                 for (int bj = 0; bj < 2; ++bj)
; #pragma unroll
;                     for (int n = 0; n < 2; ++n) { const pg8::f32x4 xi = *(const pg8::f32x4*)(xin + ro + bj * 128 + n * 16);
;                         *(pg8::f32x4*)(xout + ro + bj * 128 + n * 16) = xi + gv[bj][n] * acc[ai][bj][m][n]; } }
;     }
.LBB0_763:
	v_lshl_add_u32 v170, s56, 8, v172
	v_lshl_or_b32 v168, s58, 8, v174
	s_ashr_i32 s6, s56, 4
	v_ashrrev_i32_e32 v171, 31, v170
	s_mul_hi_i32 s27, s6, 0x6000
	s_mulk_i32 s6, 0x6000
	v_ashrrev_i32_e32 v169, 31, v168
	v_lshlrev_b64 v[166:167], 11, v[170:171]
	s_add_u32 s26, s96, s6
	v_lshl_add_u64 v[166:167], v[166:167], 0, v[168:169]
	s_addc_u32 s27, s97, s27
	v_lshlrev_b64 v[166:167], 2, v[166:167]
	v_lshl_add_u64 v[126:127], v[168:169], 2, s[26:27]
	v_lshl_add_u64 v[176:177], s[38:39], 0, v[166:167]
	global_load_dwordx4 v[142:145], v[126:127], off
	global_load_dwordx4 v[134:137], v[126:127], off offset:64
	global_load_dwordx4 v[130:133], v[126:127], off offset:512
	s_nop 0
	global_load_dwordx4 v[126:129], v[126:127], off offset:576
	s_mov_b64 s[26:27], 0x100000
	s_mov_b64 s[56:57], -1
	s_andn2_b64 vcc, exec, s[36:37]
	s_mov_b32 s92, 0x800000
	global_load_dwordx4 v[204:207], v[176:177], off
	global_load_dwordx4 v[208:211], v[176:177], off offset:64
	global_load_dwordx4 v[212:215], v[176:177], off offset:512
	global_load_dwordx4 v[216:219], v[176:177], off offset:576
	s_mov_b64 s[26:27], 0x20000
	v_lshl_add_u64 v[242:243], v[166:167], 0, s[26:27]
	v_lshl_add_u64 v[246:247], s[38:39], 0, v[242:243]
	global_load_dwordx4 v[220:223], v[246:247], off
	global_load_dwordx4 v[224:227], v[246:247], off offset:64
	global_load_dwordx4 v[228:231], v[246:247], off offset:512
	global_load_dwordx4 v[232:235], v[246:247], off offset:576
	s_waitcnt vmcnt(4)
	v_lshl_add_u64 v[244:245], s[40:41], 0, v[166:167]
	v_pk_fma_f32 v[140:141], v[140:141], v[144:145], v[206:207]
	v_pk_fma_f32 v[138:139], v[138:139], v[142:143], v[204:205]
	global_store_dwordx4 v[244:245], v[138:141], off
	v_pk_fma_f32 v[124:125], v[124:125], v[136:137], v[210:211]
	v_pk_fma_f32 v[122:123], v[122:123], v[134:135], v[208:209]
	global_store_dwordx4 v[244:245], v[122:125], off offset:64
	v_pk_fma_f32 v[120:121], v[120:121], v[132:133], v[214:215]
	v_pk_fma_f32 v[118:119], v[118:119], v[130:131], v[212:213]
	global_store_dwordx4 v[244:245], v[118:121], off offset:512
	v_pk_fma_f32 v[116:117], v[116:117], v[128:129], v[218:219]
	v_pk_fma_f32 v[114:115], v[114:115], v[126:127], v[216:217]
	global_store_dwordx4 v[244:245], v[114:117], off offset:576
	s_mov_b64 s[26:27], 0x40000
	v_lshl_add_u64 v[238:239], v[166:167], 0, s[26:27]
	v_lshl_add_u64 v[246:247], s[38:39], 0, v[238:239]
	global_load_dwordx4 v[204:207], v[246:247], off
	global_load_dwordx4 v[208:211], v[246:247], off offset:64
	global_load_dwordx4 v[212:215], v[246:247], off offset:512
	global_load_dwordx4 v[216:219], v[246:247], off offset:576
	s_waitcnt vmcnt(8)
	v_lshl_add_u64 v[244:245], s[40:41], 0, v[242:243]
	v_pk_fma_f32 v[112:113], v[112:113], v[144:145], v[222:223]
	v_pk_fma_f32 v[110:111], v[110:111], v[142:143], v[220:221]
	global_store_dwordx4 v[244:245], v[110:113], off
	v_pk_fma_f32 v[108:109], v[108:109], v[136:137], v[226:227]
	v_pk_fma_f32 v[106:107], v[106:107], v[134:135], v[224:225]
	global_store_dwordx4 v[244:245], v[106:109], off offset:64
	v_pk_fma_f32 v[104:105], v[104:105], v[132:133], v[230:231]
	v_pk_fma_f32 v[102:103], v[102:103], v[130:131], v[228:229]
	global_store_dwordx4 v[244:245], v[102:105], off offset:512
	v_pk_fma_f32 v[100:101], v[100:101], v[128:129], v[234:235]
	v_pk_fma_f32 v[98:99], v[98:99], v[126:127], v[232:233]
	global_store_dwordx4 v[244:245], v[98:101], off offset:576
	s_mov_b64 s[26:27], 0x60000
	v_lshl_add_u64 v[242:243], v[166:167], 0, s[26:27]
	v_lshl_add_u64 v[246:247], s[38:39], 0, v[242:243]
	global_load_dwordx4 v[220:223], v[246:247], off
	global_load_dwordx4 v[224:227], v[246:247], off offset:64
	global_load_dwordx4 v[228:231], v[246:247], off offset:512
	global_load_dwordx4 v[232:235], v[246:247], off offset:576
	s_waitcnt vmcnt(8)
	v_lshl_add_u64 v[244:245], s[40:41], 0, v[238:239]
	v_pk_fma_f32 v[96:97], v[96:97], v[144:145], v[206:207]
	v_pk_fma_f32 v[94:95], v[94:95], v[142:143], v[204:205]
	global_store_dwordx4 v[244:245], v[94:97], off
	v_pk_fma_f32 v[92:93], v[92:93], v[136:137], v[210:211]
	v_pk_fma_f32 v[90:91], v[90:91], v[134:135], v[208:209]
	global_store_dwordx4 v[244:245], v[90:93], off offset:64
	v_pk_fma_f32 v[88:89], v[88:89], v[132:133], v[214:215]
	v_pk_fma_f32 v[86:87], v[86:87], v[130:131], v[212:213]
	global_store_dwordx4 v[244:245], v[86:89], off offset:512
	v_pk_fma_f32 v[84:85], v[84:85], v[128:129], v[218:219]
	v_pk_fma_f32 v[82:83], v[82:83], v[126:127], v[216:217]
	global_store_dwordx4 v[244:245], v[82:85], off offset:576
	s_mov_b64 s[26:27], 0x100000
	v_lshl_add_u64 v[238:239], v[166:167], 0, s[26:27]
	v_lshl_add_u64 v[246:247], s[38:39], 0, v[238:239]
	global_load_dwordx4 v[204:207], v[246:247], off
	global_load_dwordx4 v[208:211], v[246:247], off offset:64
	global_load_dwordx4 v[212:215], v[246:247], off offset:512
	global_load_dwordx4 v[216:219], v[246:247], off offset:576
	s_waitcnt vmcnt(8)
;     __device__ __forceinline__ void operator()(const pg8::f32x4 (&acc)[2][2][4][2], const pg8::Unit& u, int wr, int wc, int fr, int fq) const {
;     ...
; #pragma unroll
;         for (int ai = 0; ai < 2; ++ai)
; #pragma unroll
;             for (int m = 0; m < 4; ++m) { const size_t ro = (size_t)(row0 + ai * 128 + m * 16) * DM + col0;
; #pragma unroll
;                 for (int bj = 0; bj < 2; ++bj)
; #pragma unroll
;                     for (int n = 0; n < 2; ++n) { const pg8::f32x4 xi = *(const pg8::f32x4*)(xin + ro + bj * 128 + n * 16);
;                         *(pg8::f32x4*)(xout + ro + bj * 128 + n * 16) = xi + gv[bj][n] * acc[ai][bj][m][n]; } }
;     }
	v_lshl_add_u64 v[244:245], s[40:41], 0, v[242:243]
	v_pk_fma_f32 v[80:81], v[80:81], v[144:145], v[222:223]
	v_pk_fma_f32 v[78:79], v[78:79], v[142:143], v[220:221]
	global_store_dwordx4 v[244:245], v[78:81], off
	v_pk_fma_f32 v[76:77], v[76:77], v[136:137], v[226:227]
	v_pk_fma_f32 v[74:75], v[74:75], v[134:135], v[224:225]
	global_store_dwordx4 v[244:245], v[74:77], off offset:64
	v_pk_fma_f32 v[72:73], v[72:73], v[132:133], v[230:231]
	v_pk_fma_f32 v[70:71], v[70:71], v[130:131], v[228:229]
	global_store_dwordx4 v[244:245], v[70:73], off offset:512
	v_pk_fma_f32 v[68:69], v[68:69], v[128:129], v[234:235]
	v_pk_fma_f32 v[66:67], v[66:67], v[126:127], v[232:233]
	global_store_dwordx4 v[244:245], v[66:69], off offset:576
	s_mov_b64 s[26:27], 0x120000
	v_lshl_add_u64 v[242:243], v[166:167], 0, s[26:27]
	v_lshl_add_u64 v[246:247], s[38:39], 0, v[242:243]
	global_load_dwordx4 v[220:223], v[246:247], off
	global_load_dwordx4 v[224:227], v[246:247], off offset:64
	global_load_dwordx4 v[228:231], v[246:247], off offset:512
	global_load_dwordx4 v[232:235], v[246:247], off offset:576
	s_waitcnt vmcnt(8)
	v_lshl_add_u64 v[244:245], s[40:41], 0, v[238:239]
	v_pk_fma_f32 v[64:65], v[64:65], v[144:145], v[206:207]
	v_pk_fma_f32 v[62:63], v[62:63], v[142:143], v[204:205]
	global_store_dwordx4 v[244:245], v[62:65], off
	v_pk_fma_f32 v[60:61], v[60:61], v[136:137], v[210:211]
	v_pk_fma_f32 v[58:59], v[58:59], v[134:135], v[208:209]
	global_store_dwordx4 v[244:245], v[58:61], off offset:64
	v_pk_fma_f32 v[56:57], v[56:57], v[132:133], v[214:215]
	v_pk_fma_f32 v[54:55], v[54:55], v[130:131], v[212:213]
	global_store_dwordx4 v[244:245], v[54:57], off offset:512
	v_pk_fma_f32 v[52:53], v[52:53], v[128:129], v[218:219]
	v_pk_fma_f32 v[50:51], v[50:51], v[126:127], v[216:217]
	global_store_dwordx4 v[244:245], v[50:53], off offset:576
	s_mov_b64 s[26:27], 0x140000
	v_lshl_add_u64 v[238:239], v[166:167], 0, s[26:27]
	v_lshl_add_u64 v[246:247], s[38:39], 0, v[238:239]
	global_load_dwordx4 v[204:207], v[246:247], off
	global_load_dwordx4 v[208:211], v[246:247], off offset:64
	global_load_dwordx4 v[212:215], v[246:247], off offset:512
	global_load_dwordx4 v[216:219], v[246:247], off offset:576
	s_waitcnt vmcnt(8)
	v_lshl_add_u64 v[244:245], s[40:41], 0, v[242:243]
	v_pk_fma_f32 v[48:49], v[48:49], v[144:145], v[222:223]
	v_pk_fma_f32 v[46:47], v[46:47], v[142:143], v[220:221]
	global_store_dwordx4 v[244:245], v[46:49], off
	v_pk_fma_f32 v[44:45], v[44:45], v[136:137], v[226:227]
	v_pk_fma_f32 v[42:43], v[42:43], v[134:135], v[224:225]
	global_store_dwordx4 v[244:245], v[42:45], off offset:64
	v_pk_fma_f32 v[40:41], v[40:41], v[132:133], v[230:231]
	v_pk_fma_f32 v[38:39], v[38:39], v[130:131], v[228:229]
	global_store_dwordx4 v[244:245], v[38:41], off offset:512
	v_pk_fma_f32 v[36:37], v[36:37], v[128:129], v[234:235]
	v_pk_fma_f32 v[34:35], v[34:35], v[126:127], v[232:233]
	global_store_dwordx4 v[244:245], v[34:37], off offset:576
	s_mov_b64 s[26:27], 0x160000
	v_lshl_add_u64 v[242:243], v[166:167], 0, s[26:27]
	v_lshl_add_u64 v[246:247], s[38:39], 0, v[242:243]
	global_load_dwordx4 v[220:223], v[246:247], off
	global_load_dwordx4 v[224:227], v[246:247], off offset:64
	global_load_dwordx4 v[228:231], v[246:247], off offset:512
	global_load_dwordx4 v[232:235], v[246:247], off offset:576
	s_waitcnt vmcnt(8)
	v_lshl_add_u64 v[244:245], s[40:41], 0, v[238:239]
	v_pk_fma_f32 v[32:33], v[32:33], v[144:145], v[206:207]
	v_pk_fma_f32 v[30:31], v[30:31], v[142:143], v[204:205]
	global_store_dwordx4 v[244:245], v[30:33], off
	v_pk_fma_f32 v[28:29], v[28:29], v[136:137], v[210:211]
	v_pk_fma_f32 v[26:27], v[26:27], v[134:135], v[208:209]
	global_store_dwordx4 v[244:245], v[26:29], off offset:64
	v_pk_fma_f32 v[24:25], v[24:25], v[132:133], v[214:215]
	v_pk_fma_f32 v[22:23], v[22:23], v[130:131], v[212:213]
	global_store_dwordx4 v[244:245], v[22:25], off offset:512
	v_pk_fma_f32 v[20:21], v[20:21], v[128:129], v[218:219]
	v_pk_fma_f32 v[18:19], v[18:19], v[126:127], v[216:217]
	global_store_dwordx4 v[244:245], v[18:21], off offset:576
	s_waitcnt vmcnt(4)
	v_lshl_add_u64 v[244:245], s[40:41], 0, v[242:243]
	v_pk_fma_f32 v[16:17], v[16:17], v[144:145], v[222:223]
	v_pk_fma_f32 v[14:15], v[14:15], v[142:143], v[220:221]
	global_store_dwordx4 v[244:245], v[14:17], off
	v_pk_fma_f32 v[12:13], v[12:13], v[136:137], v[226:227]
	v_pk_fma_f32 v[10:11], v[10:11], v[134:135], v[224:225]
	global_store_dwordx4 v[244:245], v[10:13], off offset:64
	v_pk_fma_f32 v[8:9], v[8:9], v[132:133], v[230:231]
	v_pk_fma_f32 v[6:7], v[6:7], v[130:131], v[228:229]
	global_store_dwordx4 v[244:245], v[6:9], off offset:512
	v_pk_fma_f32 v[4:5], v[4:5], v[128:129], v[234:235]
	v_pk_fma_f32 v[2:3], v[2:3], v[126:127], v[232:233]
	global_store_dwordx4 v[244:245], v[2:5], off offset:576
	s_cbranch_vccnz .LBB0_752
	s_andn2_b64 vcc, exec, s[42:43]
	s_cbranch_vccnz .LBB0_751
	s_barrier
	s_branch .LBB0_751
